# v27 + P5 mid() gate-ratio batches double-buffered (next batch loads in flight during compute)
# baseline (speedup 1.0000x reference)
; __device__ __forceinline__ float bflo(unsigned u) { return __uint_as_float(u << 16); }
; __device__ __forceinline__ float bfhi(unsigned u) { return __uint_as_float(u & 0xffff0000u); }
; __device__ __forceinline__ float frcp(float x) { return __builtin_amdgcn_rcpf(x); }
;     __device__ __forceinline__ void mid(f32x4 (&acc)[2][2][4][2], int which, int tid) const {
;         unsigned t16 = (unsigned)tid * 16u; asm volatile("" : "+v"(t16));
; #pragma unroll
;         for (int ab = 0; ab < 4; ++ab) {
;             u32x4 ga[4], gb[4];
; #pragma unroll
;             for (int m = 0; m < 4; ++m) { const unsigned char* sb = gscr + (size_t)((which * 16 + ab * 4 + m) * 8192);
;                 ga[m] = *(const u32x4*)(sb + t16); gb[m] = *(const u32x4*)(sb + 16 * 8192 + t16); }
;             __builtin_amdgcn_sched_barrier(0);
; #pragma unroll
;             for (int m = 0; m < 4; ++m) { f32x4& a0 = acc[ab >> 1][ab & 1][m][0]; f32x4& a1 = acc[ab >> 1][ab & 1][m][1];
;                 a0[0] *= (1.f + bflo(gb[m].x)) * frcp(1.f + bflo(ga[m].x)); a0[1] *= (1.f + bfhi(gb[m].x)) * frcp(1.f + bfhi(ga[m].x));
;                 a0[2] *= (1.f + bflo(gb[m].y)) * frcp(1.f + bflo(ga[m].y)); a0[3] *= (1.f + bfhi(gb[m].y)) * frcp(1.f + bfhi(ga[m].y));
;                 a1[0] *= (1.f + bflo(gb[m].z)) * frcp(1.f + bflo(ga[m].z)); a1[1] *= (1.f + bfhi(gb[m].z)) * frcp(1.f + bfhi(ga[m].z));
;                 a1[2] *= (1.f + bflo(gb[m].w)) * frcp(1.f + bflo(ga[m].w)); a1[3] *= (1.f + bfhi(gb[m].w)) * frcp(1.f + bfhi(ga[m].w)); }
.LBB0_932:
	s_andn2_b64 vcc, exec, s[24:25]
	s_cbranch_vccnz .LBB0_934
	s_cmp_eq_u32 s34, 8
	s_cselect_b32 s24, 0, 0x20000
	v_readlane_b32 s28, v252, 17
	v_readlane_b32 s29, v252, 18
	s_add_u32 s24, s28, s24
	v_mov_b32_e32 v0, v179
	s_addc_u32 s25, s29, 0
	global_load_dwordx4 v[140:143], v0, s[24:25]
	v_lshl_add_u64 v[138:139], s[24:25], 0, v[0:1]
	s_mov_b32 s24, 0x20000
	v_add_co_u32_e32 v130, vcc, s24, v138
	s_movk_i32 s24, 0x2000
	s_nop 0
	v_addc_co_u32_e32 v131, vcc, 0, v139, vcc
	global_load_dwordx4 v[144:147], v[130:131], off
	v_add_co_u32_e32 v130, vcc, s24, v138
	s_mov_b32 s24, 0x22000
	s_nop 0
	v_addc_co_u32_e32 v131, vcc, 0, v139, vcc
	global_load_dwordx4 v[148:151], v[130:131], off
	v_add_co_u32_e32 v130, vcc, s24, v138
	s_movk_i32 s24, 0x4000
	s_nop 0
	v_addc_co_u32_e32 v131, vcc, 0, v139, vcc
	global_load_dwordx4 v[152:155], v[130:131], off
	v_add_co_u32_e32 v130, vcc, s24, v138
	s_mov_b32 s24, 0x24000
	s_nop 0
	v_addc_co_u32_e32 v131, vcc, 0, v139, vcc
	global_load_dwordx4 v[156:159], v[130:131], off
	v_add_co_u32_e32 v130, vcc, s24, v138
	s_movk_i32 s24, 0x6000
	s_nop 0
	v_addc_co_u32_e32 v131, vcc, 0, v139, vcc
	global_load_dwordx4 v[160:163], v[130:131], off
	v_add_co_u32_e32 v130, vcc, s24, v138
	s_mov_b32 s24, 0x26000
	s_nop 0
	v_addc_co_u32_e32 v131, vcc, 0, v139, vcc
	v_add_co_u32_e32 v164, vcc, s24, v138
	global_load_dwordx4 v[130:133], v[130:131], off
	s_nop 0
	v_addc_co_u32_e32 v165, vcc, 0, v139, vcc
	global_load_dwordx4 v[164:167], v[164:165], off
	s_mov_b32 s24, 0x8000
	v_add_co_u32_e32 v214, vcc, s24, v138
	s_mov_b32 s24, 0x28000
	s_nop 0
	v_addc_co_u32_e32 v215, vcc, 0, v139, vcc
	v_add_co_u32_e32 v218, vcc, s24, v138
	s_mov_b32 s24, 0xa000
	s_nop 0
	v_addc_co_u32_e32 v219, vcc, 0, v139, vcc
	v_add_co_u32_e32 v222, vcc, s24, v138
	s_mov_b32 s24, 0x2a000
	s_nop 0
	v_addc_co_u32_e32 v223, vcc, 0, v139, vcc
	v_add_co_u32_e32 v226, vcc, s24, v138
	s_mov_b32 s24, 0xc000
	s_nop 0
	v_addc_co_u32_e32 v227, vcc, 0, v139, vcc
	v_add_co_u32_e32 v230, vcc, s24, v138
	s_mov_b32 s24, 0x2c000
	s_nop 0
	v_addc_co_u32_e32 v231, vcc, 0, v139, vcc
	v_add_co_u32_e32 v240, vcc, s24, v138
	s_mov_b32 s24, 0xe000
	s_nop 0
	v_addc_co_u32_e32 v241, vcc, 0, v139, vcc
	v_add_co_u32_e32 v244, vcc, s24, v138
	s_mov_b32 s24, 0x2e000
	s_nop 0
	v_addc_co_u32_e32 v245, vcc, 0, v139, vcc
	v_add_co_u32_e32 v248, vcc, s24, v138
	global_load_dwordx4 v[214:217], v[214:215], off
	s_nop 0
	global_load_dwordx4 v[218:221], v[218:219], off
	v_addc_co_u32_e32 v249, vcc, 0, v139, vcc
	global_load_dwordx4 v[222:225], v[222:223], off
	s_nop 0
	global_load_dwordx4 v[226:229], v[226:227], off
	s_nop 0
	global_load_dwordx4 v[230:233], v[230:231], off
	s_nop 0
	global_load_dwordx4 v[240:243], v[240:241], off
	s_nop 0
	global_load_dwordx4 v[244:247], v[244:245], off
	s_nop 0
	global_load_dwordx4 v[248:251], v[248:249], off
	s_waitcnt vmcnt(8)
	v_lshlrev_b32_e32 v0, 16, v140
	v_add_f32_e32 v0, 1.0, v0
	v_rcp_f32_e32 v168, v0
	v_and_b32_e32 v0, 0xffff0000, v140
	v_add_f32_e32 v0, 1.0, v0
	v_rcp_f32_e32 v169, v0
	v_lshlrev_b32_e32 v0, 16, v141
	v_add_f32_e32 v0, 1.0, v0
	v_rcp_f32_e32 v140, v0
	v_and_b32_e32 v0, 0xffff0000, v141
	v_add_f32_e32 v0, 1.0, v0
	v_rcp_f32_e32 v141, v0
	v_lshlrev_b32_e32 v170, 16, v144
	v_and_b32_e32 v171, 0xffff0000, v144
	v_lshlrev_b32_e32 v144, 16, v145
	v_and_b32_e32 v145, 0xffff0000, v145
	v_pk_add_f32 v[144:145], v[144:145], 1.0 op_sel_hi:[1,0]
	v_lshlrev_b32_e32 v0, 16, v142
	v_pk_mul_f32 v[140:141], v[144:145], v[140:141]
	v_add_f32_e32 v0, 1.0, v0
	v_pk_mul_f32 v[128:129], v[128:129], v[140:141]
	v_rcp_f32_e32 v140, v0
	v_and_b32_e32 v0, 0xffff0000, v142
	v_add_f32_e32 v0, 1.0, v0
	v_rcp_f32_e32 v141, v0
	v_lshlrev_b32_e32 v144, 16, v146
	v_and_b32_e32 v145, 0xffff0000, v146
	v_pk_add_f32 v[144:145], v[144:145], 1.0 op_sel_hi:[1,0]
	v_lshlrev_b32_e32 v0, 16, v143
	v_pk_mul_f32 v[140:141], v[144:145], v[140:141]
	v_add_f32_e32 v0, 1.0, v0
	v_pk_mul_f32 v[122:123], v[122:123], v[140:141]
	v_rcp_f32_e32 v140, v0
	v_and_b32_e32 v0, 0xffff0000, v143
	v_add_f32_e32 v0, 1.0, v0
	v_rcp_f32_e32 v141, v0
	v_lshlrev_b32_e32 v142, 16, v147
	v_and_b32_e32 v143, 0xffff0000, v147
	v_pk_add_f32 v[142:143], v[142:143], 1.0 op_sel_hi:[1,0]
	v_lshlrev_b32_e32 v0, 16, v148
	v_pk_mul_f32 v[140:141], v[142:143], v[140:141]
	v_add_f32_e32 v0, 1.0, v0
	v_pk_mul_f32 v[124:125], v[124:125], v[140:141]
	v_rcp_f32_e32 v140, v0
	v_and_b32_e32 v0, 0xffff0000, v148
	v_add_f32_e32 v0, 1.0, v0
	v_rcp_f32_e32 v141, v0
	v_lshlrev_b32_e32 v142, 16, v152
	v_and_b32_e32 v143, 0xffff0000, v152
	v_pk_add_f32 v[142:143], v[142:143], 1.0 op_sel_hi:[1,0]
	v_lshlrev_b32_e32 v0, 16, v149
	v_pk_mul_f32 v[140:141], v[142:143], v[140:141]
	v_add_f32_e32 v0, 1.0, v0
	v_pk_mul_f32 v[118:119], v[118:119], v[140:141]
	v_rcp_f32_e32 v140, v0
	v_and_b32_e32 v0, 0xffff0000, v149
	v_add_f32_e32 v0, 1.0, v0
	v_rcp_f32_e32 v141, v0
	v_lshlrev_b32_e32 v142, 16, v153
	v_and_b32_e32 v143, 0xffff0000, v153
	v_pk_add_f32 v[142:143], v[142:143], 1.0 op_sel_hi:[1,0]
	v_lshlrev_b32_e32 v0, 16, v150
	v_pk_mul_f32 v[140:141], v[142:143], v[140:141]
	v_add_f32_e32 v0, 1.0, v0
	v_pk_mul_f32 v[120:121], v[120:121], v[140:141]
	v_rcp_f32_e32 v140, v0
	v_and_b32_e32 v0, 0xffff0000, v150
	v_add_f32_e32 v0, 1.0, v0
	v_rcp_f32_e32 v141, v0
	v_lshlrev_b32_e32 v142, 16, v154
	v_and_b32_e32 v143, 0xffff0000, v154
	v_pk_add_f32 v[142:143], v[142:143], 1.0 op_sel_hi:[1,0]
	v_lshlrev_b32_e32 v0, 16, v151
	v_pk_mul_f32 v[140:141], v[142:143], v[140:141]
	v_add_f32_e32 v0, 1.0, v0
	v_pk_mul_f32 v[114:115], v[114:115], v[140:141]
	v_rcp_f32_e32 v140, v0
	v_and_b32_e32 v0, 0xffff0000, v151
	v_add_f32_e32 v0, 1.0, v0
; __device__ __forceinline__ float bflo(unsigned u) { return __uint_as_float(u << 16); }
; __device__ __forceinline__ float bfhi(unsigned u) { return __uint_as_float(u & 0xffff0000u); }
; __device__ __forceinline__ float frcp(float x) { return __builtin_amdgcn_rcpf(x); }
;     __device__ __forceinline__ void mid(f32x4 (&acc)[2][2][4][2], int which, int tid) const {
;     ...
;             for (int m = 0; m < 4; ++m) { const unsigned char* sb = gscr + (size_t)((which * 16 + ab * 4 + m) * 8192);
;                 ga[m] = *(const u32x4*)(sb + t16); gb[m] = *(const u32x4*)(sb + 16 * 8192 + t16); }
;             __builtin_amdgcn_sched_barrier(0);
; #pragma unroll
;             for (int m = 0; m < 4; ++m) { f32x4& a0 = acc[ab >> 1][ab & 1][m][0]; f32x4& a1 = acc[ab >> 1][ab & 1][m][1];
;                 a0[0] *= (1.f + bflo(gb[m].x)) * frcp(1.f + bflo(ga[m].x)); a0[1] *= (1.f + bfhi(gb[m].x)) * frcp(1.f + bfhi(ga[m].x));
;                 a0[2] *= (1.f + bflo(gb[m].y)) * frcp(1.f + bflo(ga[m].y)); a0[3] *= (1.f + bfhi(gb[m].y)) * frcp(1.f + bfhi(ga[m].y));
;                 a1[0] *= (1.f + bflo(gb[m].z)) * frcp(1.f + bflo(ga[m].z)); a1[1] *= (1.f + bfhi(gb[m].z)) * frcp(1.f + bfhi(ga[m].z));
;                 a1[2] *= (1.f + bflo(gb[m].w)) * frcp(1.f + bflo(ga[m].w)); a1[3] *= (1.f + bfhi(gb[m].w)) * frcp(1.f + bfhi(ga[m].w)); }
	v_rcp_f32_e32 v141, v0
	v_lshlrev_b32_e32 v142, 16, v155
	v_and_b32_e32 v143, 0xffff0000, v155
	v_pk_add_f32 v[142:143], v[142:143], 1.0 op_sel_hi:[1,0]
	v_lshlrev_b32_e32 v0, 16, v156
	v_pk_mul_f32 v[140:141], v[142:143], v[140:141]
	v_add_f32_e32 v0, 1.0, v0
	v_pk_mul_f32 v[116:117], v[116:117], v[140:141]
	v_rcp_f32_e32 v140, v0
	v_and_b32_e32 v0, 0xffff0000, v156
	v_add_f32_e32 v0, 1.0, v0
	v_rcp_f32_e32 v141, v0
	v_lshlrev_b32_e32 v142, 16, v160
	v_and_b32_e32 v143, 0xffff0000, v160
	v_pk_add_f32 v[142:143], v[142:143], 1.0 op_sel_hi:[1,0]
	v_lshlrev_b32_e32 v0, 16, v157
	v_pk_mul_f32 v[140:141], v[142:143], v[140:141]
	v_add_f32_e32 v0, 1.0, v0
	v_pk_mul_f32 v[110:111], v[110:111], v[140:141]
	v_rcp_f32_e32 v140, v0
	v_and_b32_e32 v0, 0xffff0000, v157
	v_add_f32_e32 v0, 1.0, v0
	v_rcp_f32_e32 v141, v0
	v_lshlrev_b32_e32 v142, 16, v161
	v_and_b32_e32 v143, 0xffff0000, v161
	v_pk_add_f32 v[142:143], v[142:143], 1.0 op_sel_hi:[1,0]
	v_lshlrev_b32_e32 v0, 16, v158
	v_pk_mul_f32 v[140:141], v[142:143], v[140:141]
	v_add_f32_e32 v0, 1.0, v0
	v_pk_mul_f32 v[112:113], v[112:113], v[140:141]
	v_rcp_f32_e32 v140, v0
	v_and_b32_e32 v0, 0xffff0000, v158
	v_add_f32_e32 v0, 1.0, v0
	v_rcp_f32_e32 v141, v0
	v_lshlrev_b32_e32 v142, 16, v162
	v_and_b32_e32 v143, 0xffff0000, v162
	v_pk_add_f32 v[142:143], v[142:143], 1.0 op_sel_hi:[1,0]
	v_lshlrev_b32_e32 v0, 16, v159
	v_pk_mul_f32 v[140:141], v[142:143], v[140:141]
	v_add_f32_e32 v0, 1.0, v0
	v_pk_mul_f32 v[106:107], v[106:107], v[140:141]
	v_rcp_f32_e32 v140, v0
	v_and_b32_e32 v0, 0xffff0000, v159
	v_add_f32_e32 v0, 1.0, v0
	v_rcp_f32_e32 v141, v0
	v_lshlrev_b32_e32 v142, 16, v163
	v_and_b32_e32 v143, 0xffff0000, v163
	v_pk_add_f32 v[142:143], v[142:143], 1.0 op_sel_hi:[1,0]
	v_lshlrev_b32_e32 v0, 16, v130
	v_pk_mul_f32 v[140:141], v[142:143], v[140:141]
	v_add_f32_e32 v0, 1.0, v0
	v_pk_mul_f32 v[108:109], v[108:109], v[140:141]
	v_rcp_f32_e32 v140, v0
	v_and_b32_e32 v0, 0xffff0000, v130
	v_add_f32_e32 v0, 1.0, v0
	v_rcp_f32_e32 v141, v0
	v_lshlrev_b32_e32 v0, 16, v131
	v_add_f32_e32 v0, 1.0, v0
	v_rcp_f32_e32 v130, v0
	v_and_b32_e32 v0, 0xffff0000, v131
	v_lshlrev_b32_e32 v142, 16, v164
	v_and_b32_e32 v143, 0xffff0000, v164
	v_add_f32_e32 v0, 1.0, v0
	v_pk_add_f32 v[142:143], v[142:143], 1.0 op_sel_hi:[1,0]
	v_rcp_f32_e32 v131, v0
	v_pk_mul_f32 v[140:141], v[142:143], v[140:141]
	v_lshlrev_b32_e32 v0, 16, v132
	v_pk_mul_f32 v[102:103], v[102:103], v[140:141]
	v_lshlrev_b32_e32 v140, 16, v165
	v_and_b32_e32 v141, 0xffff0000, v165
	v_pk_add_f32 v[140:141], v[140:141], 1.0 op_sel_hi:[1,0]
	v_add_f32_e32 v0, 1.0, v0
	v_pk_mul_f32 v[130:131], v[140:141], v[130:131]
	v_lshlrev_b32_e32 v140, 16, v166
	v_pk_mul_f32 v[104:105], v[104:105], v[130:131]
	v_rcp_f32_e32 v130, v0
	v_and_b32_e32 v0, 0xffff0000, v132
	v_add_f32_e32 v0, 1.0, v0
	v_rcp_f32_e32 v131, v0
	v_and_b32_e32 v141, 0xffff0000, v166
	v_pk_add_f32 v[140:141], v[140:141], 1.0 op_sel_hi:[1,0]
	v_lshlrev_b32_e32 v0, 16, v133
	v_pk_mul_f32 v[130:131], v[140:141], v[130:131]
	v_add_f32_e32 v0, 1.0, v0
	v_pk_mul_f32 v[98:99], v[98:99], v[130:131]
	v_rcp_f32_e32 v130, v0
	v_and_b32_e32 v0, 0xffff0000, v133
	v_add_f32_e32 v0, 1.0, v0
	v_rcp_f32_e32 v131, v0
	v_lshlrev_b32_e32 v132, 16, v167
	v_and_b32_e32 v133, 0xffff0000, v167
	v_pk_add_f32 v[170:171], v[170:171], 1.0 op_sel_hi:[1,0]
	v_pk_add_f32 v[132:133], v[132:133], 1.0 op_sel_hi:[1,0]
	v_pk_mul_f32 v[168:169], v[170:171], v[168:169]
	v_pk_mul_f32 v[130:131], v[132:133], v[130:131]
	v_pk_mul_f32 v[126:127], v[126:127], v[168:169]
	v_pk_mul_f32 v[100:101], v[100:101], v[130:131]
	v_add_co_u32_e32 v130, vcc, s55, v138
	s_mov_b32 s24, 0x30000
	s_nop 0
	v_addc_co_u32_e32 v131, vcc, 0, v139, vcc
	v_add_co_u32_e32 v140, vcc, s24, v138
	s_mov_b32 s24, 0x32000
	s_nop 0
	v_addc_co_u32_e32 v141, vcc, 0, v139, vcc
	v_add_co_u32_e32 v144, vcc, s68, v138
	global_load_dwordx4 v[130:133], v[130:131], off
	s_nop 0
	global_load_dwordx4 v[140:143], v[140:141], off
	v_addc_co_u32_e32 v145, vcc, 0, v139, vcc
	v_add_co_u32_e32 v148, vcc, s24, v138
	s_mov_b32 s24, 0x34000
	s_nop 0
	v_addc_co_u32_e32 v149, vcc, 0, v139, vcc
	v_add_co_u32_e32 v152, vcc, s69, v138
	global_load_dwordx4 v[144:147], v[144:145], off
	s_nop 0
	global_load_dwordx4 v[148:151], v[148:149], off
	v_addc_co_u32_e32 v153, vcc, 0, v139, vcc
	v_add_co_u32_e32 v156, vcc, s24, v138
	s_mov_b32 s24, 0x36000
	s_nop 0
	v_addc_co_u32_e32 v157, vcc, 0, v139, vcc
	v_add_co_u32_e32 v160, vcc, s73, v138
	global_load_dwordx4 v[152:155], v[152:153], off
	s_nop 0
	global_load_dwordx4 v[156:159], v[156:157], off
	v_addc_co_u32_e32 v161, vcc, 0, v139, vcc
	v_add_co_u32_e32 v164, vcc, s24, v138
	s_nop 1
	v_addc_co_u32_e32 v165, vcc, 0, v139, vcc
	global_load_dwordx4 v[160:163], v[160:161], off
	s_nop 0
	global_load_dwordx4 v[164:167], v[164:165], off
	s_waitcnt vmcnt(15)
	v_lshlrev_b32_e32 v0, 16, v214
	v_add_f32_e32 v0, 1.0, v0
	v_rcp_f32_e32 v168, v0
	v_and_b32_e32 v0, 0xffff0000, v214
	v_add_f32_e32 v0, 1.0, v0
	v_rcp_f32_e32 v169, v0
	v_lshlrev_b32_e32 v0, 16, v215
	v_add_f32_e32 v0, 1.0, v0
	v_rcp_f32_e32 v214, v0
	v_and_b32_e32 v0, 0xffff0000, v215
	v_add_f32_e32 v0, 1.0, v0
	v_rcp_f32_e32 v215, v0
	s_waitcnt vmcnt(14)
; __device__ __forceinline__ float bflo(unsigned u) { return __uint_as_float(u << 16); }
; __device__ __forceinline__ float bfhi(unsigned u) { return __uint_as_float(u & 0xffff0000u); }
; __device__ __forceinline__ float frcp(float x) { return __builtin_amdgcn_rcpf(x); }
;     __device__ __forceinline__ void mid(f32x4 (&acc)[2][2][4][2], int which, int tid) const {
;     ...
;             for (int m = 0; m < 4; ++m) { f32x4& a0 = acc[ab >> 1][ab & 1][m][0]; f32x4& a1 = acc[ab >> 1][ab & 1][m][1];
;                 a0[0] *= (1.f + bflo(gb[m].x)) * frcp(1.f + bflo(ga[m].x)); a0[1] *= (1.f + bfhi(gb[m].x)) * frcp(1.f + bfhi(ga[m].x));
;                 a0[2] *= (1.f + bflo(gb[m].y)) * frcp(1.f + bflo(ga[m].y)); a0[3] *= (1.f + bfhi(gb[m].y)) * frcp(1.f + bfhi(ga[m].y));
;                 a1[0] *= (1.f + bflo(gb[m].z)) * frcp(1.f + bflo(ga[m].z)); a1[1] *= (1.f + bfhi(gb[m].z)) * frcp(1.f + bfhi(ga[m].z));
;                 a1[2] *= (1.f + bflo(gb[m].w)) * frcp(1.f + bflo(ga[m].w)); a1[3] *= (1.f + bfhi(gb[m].w)) * frcp(1.f + bfhi(ga[m].w)); }
	v_lshlrev_b32_e32 v170, 16, v218
	v_and_b32_e32 v171, 0xffff0000, v218
	v_lshlrev_b32_e32 v218, 16, v219
	v_and_b32_e32 v219, 0xffff0000, v219
	v_pk_add_f32 v[218:219], v[218:219], 1.0 op_sel_hi:[1,0]
	v_lshlrev_b32_e32 v0, 16, v216
	v_pk_mul_f32 v[214:215], v[218:219], v[214:215]
	v_add_f32_e32 v0, 1.0, v0
	v_pk_mul_f32 v[96:97], v[96:97], v[214:215]
	v_rcp_f32_e32 v214, v0
	v_and_b32_e32 v0, 0xffff0000, v216
	v_add_f32_e32 v0, 1.0, v0
	v_rcp_f32_e32 v215, v0
	v_lshlrev_b32_e32 v218, 16, v220
	v_and_b32_e32 v219, 0xffff0000, v220
	v_pk_add_f32 v[218:219], v[218:219], 1.0 op_sel_hi:[1,0]
	v_lshlrev_b32_e32 v0, 16, v217
	v_pk_mul_f32 v[214:215], v[218:219], v[214:215]
	v_add_f32_e32 v0, 1.0, v0
	v_pk_mul_f32 v[90:91], v[90:91], v[214:215]
	v_rcp_f32_e32 v214, v0
	v_and_b32_e32 v0, 0xffff0000, v217
	v_add_f32_e32 v0, 1.0, v0
	v_rcp_f32_e32 v215, v0
	v_lshlrev_b32_e32 v216, 16, v221
	v_and_b32_e32 v217, 0xffff0000, v221
	v_pk_add_f32 v[216:217], v[216:217], 1.0 op_sel_hi:[1,0]
	s_waitcnt vmcnt(13)
	v_lshlrev_b32_e32 v0, 16, v222
	v_pk_mul_f32 v[214:215], v[216:217], v[214:215]
	v_add_f32_e32 v0, 1.0, v0
	v_pk_mul_f32 v[92:93], v[92:93], v[214:215]
	v_rcp_f32_e32 v214, v0
	v_and_b32_e32 v0, 0xffff0000, v222
	v_add_f32_e32 v0, 1.0, v0
	v_rcp_f32_e32 v215, v0
	s_waitcnt vmcnt(12)
	v_lshlrev_b32_e32 v216, 16, v226
	v_and_b32_e32 v217, 0xffff0000, v226
	v_pk_add_f32 v[216:217], v[216:217], 1.0 op_sel_hi:[1,0]
	v_lshlrev_b32_e32 v0, 16, v223
	v_pk_mul_f32 v[214:215], v[216:217], v[214:215]
	v_add_f32_e32 v0, 1.0, v0
	v_pk_mul_f32 v[86:87], v[86:87], v[214:215]
	v_rcp_f32_e32 v214, v0
	v_and_b32_e32 v0, 0xffff0000, v223
	v_add_f32_e32 v0, 1.0, v0
	v_rcp_f32_e32 v215, v0
	v_lshlrev_b32_e32 v216, 16, v227
	v_and_b32_e32 v217, 0xffff0000, v227
	v_pk_add_f32 v[216:217], v[216:217], 1.0 op_sel_hi:[1,0]
	v_lshlrev_b32_e32 v0, 16, v224
	v_pk_mul_f32 v[214:215], v[216:217], v[214:215]
	v_add_f32_e32 v0, 1.0, v0
	v_pk_mul_f32 v[88:89], v[88:89], v[214:215]
	v_rcp_f32_e32 v214, v0
	v_and_b32_e32 v0, 0xffff0000, v224
	v_add_f32_e32 v0, 1.0, v0
	v_rcp_f32_e32 v215, v0
	v_lshlrev_b32_e32 v216, 16, v228
	v_and_b32_e32 v217, 0xffff0000, v228
	v_pk_add_f32 v[216:217], v[216:217], 1.0 op_sel_hi:[1,0]
	v_lshlrev_b32_e32 v0, 16, v225
	v_pk_mul_f32 v[214:215], v[216:217], v[214:215]
	v_add_f32_e32 v0, 1.0, v0
	v_pk_mul_f32 v[82:83], v[82:83], v[214:215]
	v_rcp_f32_e32 v214, v0
	v_and_b32_e32 v0, 0xffff0000, v225
	v_add_f32_e32 v0, 1.0, v0
	v_rcp_f32_e32 v215, v0
	v_lshlrev_b32_e32 v216, 16, v229
	v_and_b32_e32 v217, 0xffff0000, v229
	v_pk_add_f32 v[216:217], v[216:217], 1.0 op_sel_hi:[1,0]
	s_waitcnt vmcnt(11)
	v_lshlrev_b32_e32 v0, 16, v230
	v_pk_mul_f32 v[214:215], v[216:217], v[214:215]
	v_add_f32_e32 v0, 1.0, v0
	v_pk_mul_f32 v[84:85], v[84:85], v[214:215]
	v_rcp_f32_e32 v214, v0
	v_and_b32_e32 v0, 0xffff0000, v230
	v_add_f32_e32 v0, 1.0, v0
	v_rcp_f32_e32 v215, v0
	s_waitcnt vmcnt(10)
	v_lshlrev_b32_e32 v216, 16, v240
	v_and_b32_e32 v217, 0xffff0000, v240
	v_pk_add_f32 v[216:217], v[216:217], 1.0 op_sel_hi:[1,0]
	v_lshlrev_b32_e32 v0, 16, v231
	v_pk_mul_f32 v[214:215], v[216:217], v[214:215]
	v_add_f32_e32 v0, 1.0, v0
	v_pk_mul_f32 v[78:79], v[78:79], v[214:215]
	v_rcp_f32_e32 v214, v0
	v_and_b32_e32 v0, 0xffff0000, v231
	v_add_f32_e32 v0, 1.0, v0
	v_rcp_f32_e32 v215, v0
	v_lshlrev_b32_e32 v216, 16, v241
	v_and_b32_e32 v217, 0xffff0000, v241
	v_pk_add_f32 v[216:217], v[216:217], 1.0 op_sel_hi:[1,0]
	v_lshlrev_b32_e32 v0, 16, v232
	v_pk_mul_f32 v[214:215], v[216:217], v[214:215]
	v_add_f32_e32 v0, 1.0, v0
	v_pk_mul_f32 v[80:81], v[80:81], v[214:215]
	v_rcp_f32_e32 v214, v0
	v_and_b32_e32 v0, 0xffff0000, v232
	v_add_f32_e32 v0, 1.0, v0
	v_rcp_f32_e32 v215, v0
	v_lshlrev_b32_e32 v216, 16, v242
	v_and_b32_e32 v217, 0xffff0000, v242
	v_pk_add_f32 v[216:217], v[216:217], 1.0 op_sel_hi:[1,0]
	v_lshlrev_b32_e32 v0, 16, v233
	v_pk_mul_f32 v[214:215], v[216:217], v[214:215]
	v_add_f32_e32 v0, 1.0, v0
	v_pk_mul_f32 v[74:75], v[74:75], v[214:215]
	v_rcp_f32_e32 v214, v0
	v_and_b32_e32 v0, 0xffff0000, v233
	v_add_f32_e32 v0, 1.0, v0
	v_rcp_f32_e32 v215, v0
	v_lshlrev_b32_e32 v216, 16, v243
	v_and_b32_e32 v217, 0xffff0000, v243
	v_pk_add_f32 v[216:217], v[216:217], 1.0 op_sel_hi:[1,0]
	s_waitcnt vmcnt(9)
	v_lshlrev_b32_e32 v0, 16, v244
	v_pk_mul_f32 v[214:215], v[216:217], v[214:215]
	v_add_f32_e32 v0, 1.0, v0
	v_pk_mul_f32 v[76:77], v[76:77], v[214:215]
	v_rcp_f32_e32 v214, v0
	v_and_b32_e32 v0, 0xffff0000, v244
	v_add_f32_e32 v0, 1.0, v0
	v_rcp_f32_e32 v215, v0
	s_waitcnt vmcnt(8)
; __device__ __forceinline__ float bflo(unsigned u) { return __uint_as_float(u << 16); }
; __device__ __forceinline__ float bfhi(unsigned u) { return __uint_as_float(u & 0xffff0000u); }
; __device__ __forceinline__ float frcp(float x) { return __builtin_amdgcn_rcpf(x); }
;     __device__ __forceinline__ void mid(f32x4 (&acc)[2][2][4][2], int which, int tid) const {
;     ...
;             for (int m = 0; m < 4; ++m) { const unsigned char* sb = gscr + (size_t)((which * 16 + ab * 4 + m) * 8192);
;                 ga[m] = *(const u32x4*)(sb + t16); gb[m] = *(const u32x4*)(sb + 16 * 8192 + t16); }
;             __builtin_amdgcn_sched_barrier(0);
; #pragma unroll
;             for (int m = 0; m < 4; ++m) { f32x4& a0 = acc[ab >> 1][ab & 1][m][0]; f32x4& a1 = acc[ab >> 1][ab & 1][m][1];
;                 a0[0] *= (1.f + bflo(gb[m].x)) * frcp(1.f + bflo(ga[m].x)); a0[1] *= (1.f + bfhi(gb[m].x)) * frcp(1.f + bfhi(ga[m].x));
;                 a0[2] *= (1.f + bflo(gb[m].y)) * frcp(1.f + bflo(ga[m].y)); a0[3] *= (1.f + bfhi(gb[m].y)) * frcp(1.f + bfhi(ga[m].y));
;                 a1[0] *= (1.f + bflo(gb[m].z)) * frcp(1.f + bflo(ga[m].z)); a1[1] *= (1.f + bfhi(gb[m].z)) * frcp(1.f + bfhi(ga[m].z));
;                 a1[2] *= (1.f + bflo(gb[m].w)) * frcp(1.f + bflo(ga[m].w)); a1[3] *= (1.f + bfhi(gb[m].w)) * frcp(1.f + bfhi(ga[m].w)); }
	v_lshlrev_b32_e32 v216, 16, v248
	v_and_b32_e32 v217, 0xffff0000, v248
	v_pk_add_f32 v[216:217], v[216:217], 1.0 op_sel_hi:[1,0]
	v_lshlrev_b32_e32 v0, 16, v245
	v_pk_mul_f32 v[214:215], v[216:217], v[214:215]
	v_add_f32_e32 v0, 1.0, v0
	v_pk_mul_f32 v[70:71], v[70:71], v[214:215]
	v_rcp_f32_e32 v214, v0
	v_and_b32_e32 v0, 0xffff0000, v245
	v_add_f32_e32 v0, 1.0, v0
	v_rcp_f32_e32 v215, v0
	v_lshlrev_b32_e32 v216, 16, v249
	v_and_b32_e32 v217, 0xffff0000, v249
	v_pk_add_f32 v[216:217], v[216:217], 1.0 op_sel_hi:[1,0]
	v_lshlrev_b32_e32 v0, 16, v246
	v_pk_mul_f32 v[214:215], v[216:217], v[214:215]
	v_add_f32_e32 v0, 1.0, v0
	v_pk_mul_f32 v[72:73], v[72:73], v[214:215]
	v_rcp_f32_e32 v214, v0
	v_and_b32_e32 v0, 0xffff0000, v246
	v_add_f32_e32 v0, 1.0, v0
	v_rcp_f32_e32 v215, v0
	v_lshlrev_b32_e32 v216, 16, v250
	v_and_b32_e32 v217, 0xffff0000, v250
	v_pk_add_f32 v[216:217], v[216:217], 1.0 op_sel_hi:[1,0]
	v_lshlrev_b32_e32 v0, 16, v247
	v_pk_mul_f32 v[214:215], v[216:217], v[214:215]
	v_add_f32_e32 v0, 1.0, v0
	v_pk_mul_f32 v[66:67], v[66:67], v[214:215]
	v_rcp_f32_e32 v214, v0
	v_and_b32_e32 v0, 0xffff0000, v247
	v_add_f32_e32 v0, 1.0, v0
	v_rcp_f32_e32 v215, v0
	v_lshlrev_b32_e32 v216, 16, v251
	v_and_b32_e32 v217, 0xffff0000, v251
	v_pk_add_f32 v[170:171], v[170:171], 1.0 op_sel_hi:[1,0]
	v_pk_add_f32 v[216:217], v[216:217], 1.0 op_sel_hi:[1,0]
	v_pk_mul_f32 v[168:169], v[170:171], v[168:169]
	v_pk_mul_f32 v[214:215], v[216:217], v[214:215]
	v_pk_mul_f32 v[94:95], v[94:95], v[168:169]
	v_pk_mul_f32 v[68:69], v[68:69], v[214:215]
	s_mov_b32 s24, 0x18000
	v_add_co_u32_e32 v214, vcc, s24, v138
	s_mov_b32 s24, 0x38000
	s_nop 0
	v_addc_co_u32_e32 v215, vcc, 0, v139, vcc
	v_add_co_u32_e32 v218, vcc, s24, v138
	s_mov_b32 s24, 0x1a000
	s_nop 0
	v_addc_co_u32_e32 v219, vcc, 0, v139, vcc
	v_add_co_u32_e32 v222, vcc, s24, v138
	s_mov_b32 s24, 0x3a000
	s_nop 0
	v_addc_co_u32_e32 v223, vcc, 0, v139, vcc
	v_add_co_u32_e32 v226, vcc, s24, v138
	s_mov_b32 s24, 0x1c000
	s_nop 0
	v_addc_co_u32_e32 v227, vcc, 0, v139, vcc
	v_add_co_u32_e32 v230, vcc, s24, v138
	s_mov_b32 s24, 0x3c000
	s_nop 0
	v_addc_co_u32_e32 v231, vcc, 0, v139, vcc
	v_add_co_u32_e32 v240, vcc, s24, v138
	s_mov_b32 s24, 0x1e000
	s_nop 0
	v_addc_co_u32_e32 v241, vcc, 0, v139, vcc
	v_add_co_u32_e32 v244, vcc, s24, v138
	s_mov_b32 s24, 0x3e000
	s_nop 0
	v_addc_co_u32_e32 v245, vcc, 0, v139, vcc
	v_add_co_u32_e32 v138, vcc, s24, v138
	global_load_dwordx4 v[214:217], v[214:215], off
	s_nop 0
	global_load_dwordx4 v[218:221], v[218:219], off
	s_nop 0
	global_load_dwordx4 v[222:225], v[222:223], off
	s_nop 0
	global_load_dwordx4 v[226:229], v[226:227], off
	s_nop 0
	global_load_dwordx4 v[230:233], v[230:231], off
	s_nop 0
	global_load_dwordx4 v[240:243], v[240:241], off
	v_addc_co_u32_e32 v139, vcc, 0, v139, vcc
	global_load_dwordx4 v[244:247], v[244:245], off
	s_nop 0
	global_load_dwordx4 v[248:251], v[138:139], off
	s_waitcnt vmcnt(15)
	v_lshlrev_b32_e32 v0, 16, v130
	v_add_f32_e32 v0, 1.0, v0
	v_rcp_f32_e32 v168, v0
	v_and_b32_e32 v0, 0xffff0000, v130
	v_add_f32_e32 v0, 1.0, v0
	v_rcp_f32_e32 v169, v0
	v_lshlrev_b32_e32 v0, 16, v131
	v_add_f32_e32 v0, 1.0, v0
	v_rcp_f32_e32 v130, v0
	v_and_b32_e32 v0, 0xffff0000, v131
	v_add_f32_e32 v0, 1.0, v0
	v_rcp_f32_e32 v131, v0
	s_waitcnt vmcnt(14)
	v_lshlrev_b32_e32 v170, 16, v140
	v_and_b32_e32 v171, 0xffff0000, v140
	v_lshlrev_b32_e32 v140, 16, v141
	v_and_b32_e32 v141, 0xffff0000, v141
	v_pk_add_f32 v[140:141], v[140:141], 1.0 op_sel_hi:[1,0]
	v_lshlrev_b32_e32 v0, 16, v132
	v_pk_mul_f32 v[130:131], v[140:141], v[130:131]
	v_add_f32_e32 v0, 1.0, v0
	v_pk_mul_f32 v[64:65], v[64:65], v[130:131]
	v_rcp_f32_e32 v130, v0
	v_and_b32_e32 v0, 0xffff0000, v132
	v_add_f32_e32 v0, 1.0, v0
	v_rcp_f32_e32 v131, v0
	v_lshlrev_b32_e32 v140, 16, v142
	v_and_b32_e32 v141, 0xffff0000, v142
	v_pk_add_f32 v[140:141], v[140:141], 1.0 op_sel_hi:[1,0]
	v_lshlrev_b32_e32 v0, 16, v133
	v_pk_mul_f32 v[130:131], v[140:141], v[130:131]
	v_add_f32_e32 v0, 1.0, v0
	v_pk_mul_f32 v[58:59], v[58:59], v[130:131]
	v_rcp_f32_e32 v130, v0
	v_and_b32_e32 v0, 0xffff0000, v133
	v_add_f32_e32 v0, 1.0, v0
	v_rcp_f32_e32 v131, v0
	v_lshlrev_b32_e32 v132, 16, v143
	v_and_b32_e32 v133, 0xffff0000, v143
	v_pk_add_f32 v[132:133], v[132:133], 1.0 op_sel_hi:[1,0]
	s_waitcnt vmcnt(13)
	v_lshlrev_b32_e32 v0, 16, v144
	v_pk_mul_f32 v[130:131], v[132:133], v[130:131]
	v_add_f32_e32 v0, 1.0, v0
	v_pk_mul_f32 v[60:61], v[60:61], v[130:131]
	v_rcp_f32_e32 v130, v0
	v_and_b32_e32 v0, 0xffff0000, v144
	v_add_f32_e32 v0, 1.0, v0
	v_rcp_f32_e32 v131, v0
	s_waitcnt vmcnt(12)
	v_lshlrev_b32_e32 v132, 16, v148
	v_and_b32_e32 v133, 0xffff0000, v148
	v_pk_add_f32 v[132:133], v[132:133], 1.0 op_sel_hi:[1,0]
	v_lshlrev_b32_e32 v0, 16, v145
	v_pk_mul_f32 v[130:131], v[132:133], v[130:131]
	v_add_f32_e32 v0, 1.0, v0
	v_pk_mul_f32 v[54:55], v[54:55], v[130:131]
	v_rcp_f32_e32 v130, v0
	v_and_b32_e32 v0, 0xffff0000, v145
	v_add_f32_e32 v0, 1.0, v0
	v_rcp_f32_e32 v131, v0
	v_lshlrev_b32_e32 v132, 16, v149
	v_and_b32_e32 v133, 0xffff0000, v149
	v_pk_add_f32 v[132:133], v[132:133], 1.0 op_sel_hi:[1,0]
	v_lshlrev_b32_e32 v0, 16, v146
	v_pk_mul_f32 v[130:131], v[132:133], v[130:131]
	v_add_f32_e32 v0, 1.0, v0
	v_pk_mul_f32 v[56:57], v[56:57], v[130:131]
	v_rcp_f32_e32 v130, v0
	v_and_b32_e32 v0, 0xffff0000, v146
	v_add_f32_e32 v0, 1.0, v0
	v_rcp_f32_e32 v131, v0
	v_lshlrev_b32_e32 v132, 16, v150
	v_and_b32_e32 v133, 0xffff0000, v150
	v_pk_add_f32 v[132:133], v[132:133], 1.0 op_sel_hi:[1,0]
	v_lshlrev_b32_e32 v0, 16, v147
	v_pk_mul_f32 v[130:131], v[132:133], v[130:131]
	v_add_f32_e32 v0, 1.0, v0
	v_pk_mul_f32 v[50:51], v[50:51], v[130:131]
	v_rcp_f32_e32 v130, v0
	v_and_b32_e32 v0, 0xffff0000, v147
	v_add_f32_e32 v0, 1.0, v0
	v_rcp_f32_e32 v131, v0
	v_lshlrev_b32_e32 v132, 16, v151
	v_and_b32_e32 v133, 0xffff0000, v151
	v_pk_add_f32 v[132:133], v[132:133], 1.0 op_sel_hi:[1,0]
	s_waitcnt vmcnt(11)
; __device__ __forceinline__ float bflo(unsigned u) { return __uint_as_float(u << 16); }
; __device__ __forceinline__ float bfhi(unsigned u) { return __uint_as_float(u & 0xffff0000u); }
; __device__ __forceinline__ float frcp(float x) { return __builtin_amdgcn_rcpf(x); }
;     __device__ __forceinline__ void mid(f32x4 (&acc)[2][2][4][2], int which, int tid) const {
;     ...
;             for (int m = 0; m < 4; ++m) { const unsigned char* sb = gscr + (size_t)((which * 16 + ab * 4 + m) * 8192);
;                 ga[m] = *(const u32x4*)(sb + t16); gb[m] = *(const u32x4*)(sb + 16 * 8192 + t16); }
;             __builtin_amdgcn_sched_barrier(0);
; #pragma unroll
;             for (int m = 0; m < 4; ++m) { f32x4& a0 = acc[ab >> 1][ab & 1][m][0]; f32x4& a1 = acc[ab >> 1][ab & 1][m][1];
;                 a0[0] *= (1.f + bflo(gb[m].x)) * frcp(1.f + bflo(ga[m].x)); a0[1] *= (1.f + bfhi(gb[m].x)) * frcp(1.f + bfhi(ga[m].x));
;                 a0[2] *= (1.f + bflo(gb[m].y)) * frcp(1.f + bflo(ga[m].y)); a0[3] *= (1.f + bfhi(gb[m].y)) * frcp(1.f + bfhi(ga[m].y));
;                 a1[0] *= (1.f + bflo(gb[m].z)) * frcp(1.f + bflo(ga[m].z)); a1[1] *= (1.f + bfhi(gb[m].z)) * frcp(1.f + bfhi(ga[m].z));
;                 a1[2] *= (1.f + bflo(gb[m].w)) * frcp(1.f + bflo(ga[m].w)); a1[3] *= (1.f + bfhi(gb[m].w)) * frcp(1.f + bfhi(ga[m].w)); }
	v_lshlrev_b32_e32 v0, 16, v152
	v_pk_mul_f32 v[130:131], v[132:133], v[130:131]
	v_add_f32_e32 v0, 1.0, v0
	v_pk_mul_f32 v[52:53], v[52:53], v[130:131]
	v_rcp_f32_e32 v130, v0
	v_and_b32_e32 v0, 0xffff0000, v152
	v_add_f32_e32 v0, 1.0, v0
	v_rcp_f32_e32 v131, v0
	s_waitcnt vmcnt(10)
	v_lshlrev_b32_e32 v132, 16, v156
	v_and_b32_e32 v133, 0xffff0000, v156
	v_pk_add_f32 v[132:133], v[132:133], 1.0 op_sel_hi:[1,0]
	v_lshlrev_b32_e32 v0, 16, v153
	v_pk_mul_f32 v[130:131], v[132:133], v[130:131]
	v_add_f32_e32 v0, 1.0, v0
	v_pk_mul_f32 v[46:47], v[46:47], v[130:131]
	v_rcp_f32_e32 v130, v0
	v_and_b32_e32 v0, 0xffff0000, v153
	v_add_f32_e32 v0, 1.0, v0
	v_rcp_f32_e32 v131, v0
	v_lshlrev_b32_e32 v132, 16, v157
	v_and_b32_e32 v133, 0xffff0000, v157
	v_pk_add_f32 v[132:133], v[132:133], 1.0 op_sel_hi:[1,0]
	v_lshlrev_b32_e32 v0, 16, v154
	v_pk_mul_f32 v[130:131], v[132:133], v[130:131]
	v_add_f32_e32 v0, 1.0, v0
	v_pk_mul_f32 v[48:49], v[48:49], v[130:131]
	v_rcp_f32_e32 v130, v0
	v_and_b32_e32 v0, 0xffff0000, v154
	v_add_f32_e32 v0, 1.0, v0
	v_rcp_f32_e32 v131, v0
	v_lshlrev_b32_e32 v132, 16, v158
	v_and_b32_e32 v133, 0xffff0000, v158
	v_pk_add_f32 v[132:133], v[132:133], 1.0 op_sel_hi:[1,0]
	v_lshlrev_b32_e32 v0, 16, v155
	v_pk_mul_f32 v[130:131], v[132:133], v[130:131]
	v_add_f32_e32 v0, 1.0, v0
	v_pk_mul_f32 v[42:43], v[42:43], v[130:131]
	v_rcp_f32_e32 v130, v0
	v_and_b32_e32 v0, 0xffff0000, v155
	v_add_f32_e32 v0, 1.0, v0
	v_rcp_f32_e32 v131, v0
	v_lshlrev_b32_e32 v132, 16, v159
	v_and_b32_e32 v133, 0xffff0000, v159
	v_pk_add_f32 v[132:133], v[132:133], 1.0 op_sel_hi:[1,0]
	s_waitcnt vmcnt(9)
	v_lshlrev_b32_e32 v0, 16, v160
	v_pk_mul_f32 v[130:131], v[132:133], v[130:131]
	v_add_f32_e32 v0, 1.0, v0
	v_pk_mul_f32 v[44:45], v[44:45], v[130:131]
	v_rcp_f32_e32 v130, v0
	v_and_b32_e32 v0, 0xffff0000, v160
	v_add_f32_e32 v0, 1.0, v0
	v_rcp_f32_e32 v131, v0
	s_waitcnt vmcnt(8)
	v_lshlrev_b32_e32 v132, 16, v164
	v_and_b32_e32 v133, 0xffff0000, v164
	v_pk_add_f32 v[132:133], v[132:133], 1.0 op_sel_hi:[1,0]
	v_lshlrev_b32_e32 v0, 16, v161
	v_pk_mul_f32 v[130:131], v[132:133], v[130:131]
	v_add_f32_e32 v0, 1.0, v0
	v_pk_mul_f32 v[38:39], v[38:39], v[130:131]
	v_rcp_f32_e32 v130, v0
	v_and_b32_e32 v0, 0xffff0000, v161
	v_add_f32_e32 v0, 1.0, v0
	v_rcp_f32_e32 v131, v0
	v_lshlrev_b32_e32 v132, 16, v165
	v_and_b32_e32 v133, 0xffff0000, v165
	v_pk_add_f32 v[132:133], v[132:133], 1.0 op_sel_hi:[1,0]
	v_lshlrev_b32_e32 v0, 16, v162
	v_pk_mul_f32 v[130:131], v[132:133], v[130:131]
	v_add_f32_e32 v0, 1.0, v0
	v_pk_mul_f32 v[40:41], v[40:41], v[130:131]
	v_rcp_f32_e32 v130, v0
	v_and_b32_e32 v0, 0xffff0000, v162
	v_add_f32_e32 v0, 1.0, v0
	v_rcp_f32_e32 v131, v0
	v_lshlrev_b32_e32 v132, 16, v166
	v_and_b32_e32 v133, 0xffff0000, v166
	v_pk_add_f32 v[132:133], v[132:133], 1.0 op_sel_hi:[1,0]
	v_lshlrev_b32_e32 v0, 16, v163
	v_pk_mul_f32 v[130:131], v[132:133], v[130:131]
	v_add_f32_e32 v0, 1.0, v0
	v_pk_mul_f32 v[34:35], v[34:35], v[130:131]
	v_rcp_f32_e32 v130, v0
	v_and_b32_e32 v0, 0xffff0000, v163
	v_add_f32_e32 v0, 1.0, v0
	v_rcp_f32_e32 v131, v0
	v_lshlrev_b32_e32 v132, 16, v167
	v_and_b32_e32 v133, 0xffff0000, v167
	v_pk_add_f32 v[170:171], v[170:171], 1.0 op_sel_hi:[1,0]
	v_pk_add_f32 v[132:133], v[132:133], 1.0 op_sel_hi:[1,0]
	v_pk_mul_f32 v[168:169], v[170:171], v[168:169]
	v_pk_mul_f32 v[130:131], v[132:133], v[130:131]
	v_pk_mul_f32 v[62:63], v[62:63], v[168:169]
	v_pk_mul_f32 v[36:37], v[36:37], v[130:131]
	s_waitcnt vmcnt(7)
	v_lshlrev_b32_e32 v0, 16, v214
	v_add_f32_e32 v0, 1.0, v0
	v_rcp_f32_e32 v138, v0
	v_and_b32_e32 v0, 0xffff0000, v214
	v_add_f32_e32 v0, 1.0, v0
	v_rcp_f32_e32 v139, v0
	v_lshlrev_b32_e32 v0, 16, v215
	v_add_f32_e32 v0, 1.0, v0
	v_rcp_f32_e32 v214, v0
	v_and_b32_e32 v0, 0xffff0000, v215
	s_waitcnt vmcnt(6)
	v_lshlrev_b32_e32 v168, 16, v218
	v_and_b32_e32 v169, 0xffff0000, v218
	v_add_f32_e32 v0, 1.0, v0
	v_pk_add_f32 v[168:169], v[168:169], 1.0 op_sel_hi:[1,0]
	v_rcp_f32_e32 v215, v0
	v_pk_mul_f32 v[138:139], v[168:169], v[138:139]
	v_lshlrev_b32_e32 v0, 16, v216
	v_pk_mul_f32 v[30:31], v[30:31], v[138:139]
	v_lshlrev_b32_e32 v138, 16, v219
	v_and_b32_e32 v139, 0xffff0000, v219
	v_pk_add_f32 v[138:139], v[138:139], 1.0 op_sel_hi:[1,0]
	v_add_f32_e32 v0, 1.0, v0
	v_pk_mul_f32 v[214:215], v[138:139], v[214:215]
	v_lshlrev_b32_e32 v138, 16, v220
	v_pk_mul_f32 v[32:33], v[32:33], v[214:215]
	v_rcp_f32_e32 v214, v0
	v_and_b32_e32 v0, 0xffff0000, v216
	v_add_f32_e32 v0, 1.0, v0
	v_rcp_f32_e32 v215, v0
	v_and_b32_e32 v139, 0xffff0000, v220
	v_pk_add_f32 v[138:139], v[138:139], 1.0 op_sel_hi:[1,0]
	v_lshlrev_b32_e32 v0, 16, v217
	v_pk_mul_f32 v[214:215], v[138:139], v[214:215]
	v_add_f32_e32 v0, 1.0, v0
	v_pk_mul_f32 v[26:27], v[26:27], v[214:215]
	v_rcp_f32_e32 v214, v0
	v_and_b32_e32 v0, 0xffff0000, v217
	v_add_f32_e32 v0, 1.0, v0
	v_rcp_f32_e32 v215, v0
	v_lshlrev_b32_e32 v216, 16, v221
	v_and_b32_e32 v217, 0xffff0000, v221
	v_pk_add_f32 v[216:217], v[216:217], 1.0 op_sel_hi:[1,0]
	s_waitcnt vmcnt(5)
; __device__ __forceinline__ float bflo(unsigned u) { return __uint_as_float(u << 16); }
; __device__ __forceinline__ float bfhi(unsigned u) { return __uint_as_float(u & 0xffff0000u); }
; __device__ __forceinline__ float frcp(float x) { return __builtin_amdgcn_rcpf(x); }
;     __device__ __forceinline__ void mid(f32x4 (&acc)[2][2][4][2], int which, int tid) const {
;     ...
;             for (int m = 0; m < 4; ++m) { f32x4& a0 = acc[ab >> 1][ab & 1][m][0]; f32x4& a1 = acc[ab >> 1][ab & 1][m][1];
;                 a0[0] *= (1.f + bflo(gb[m].x)) * frcp(1.f + bflo(ga[m].x)); a0[1] *= (1.f + bfhi(gb[m].x)) * frcp(1.f + bfhi(ga[m].x));
;                 a0[2] *= (1.f + bflo(gb[m].y)) * frcp(1.f + bflo(ga[m].y)); a0[3] *= (1.f + bfhi(gb[m].y)) * frcp(1.f + bfhi(ga[m].y));
;                 a1[0] *= (1.f + bflo(gb[m].z)) * frcp(1.f + bflo(ga[m].z)); a1[1] *= (1.f + bfhi(gb[m].z)) * frcp(1.f + bfhi(ga[m].z));
;                 a1[2] *= (1.f + bflo(gb[m].w)) * frcp(1.f + bflo(ga[m].w)); a1[3] *= (1.f + bfhi(gb[m].w)) * frcp(1.f + bfhi(ga[m].w)); }
	v_lshlrev_b32_e32 v0, 16, v222
	v_pk_mul_f32 v[214:215], v[216:217], v[214:215]
	v_add_f32_e32 v0, 1.0, v0
	v_pk_mul_f32 v[28:29], v[28:29], v[214:215]
	v_rcp_f32_e32 v214, v0
	v_and_b32_e32 v0, 0xffff0000, v222
	v_add_f32_e32 v0, 1.0, v0
	v_rcp_f32_e32 v215, v0
	s_waitcnt vmcnt(4)
	v_lshlrev_b32_e32 v216, 16, v226
	v_and_b32_e32 v217, 0xffff0000, v226
	v_pk_add_f32 v[216:217], v[216:217], 1.0 op_sel_hi:[1,0]
	v_lshlrev_b32_e32 v0, 16, v223
	v_pk_mul_f32 v[214:215], v[216:217], v[214:215]
	v_add_f32_e32 v0, 1.0, v0
	v_pk_mul_f32 v[22:23], v[22:23], v[214:215]
	v_rcp_f32_e32 v214, v0
	v_and_b32_e32 v0, 0xffff0000, v223
	v_add_f32_e32 v0, 1.0, v0
	v_rcp_f32_e32 v215, v0
	v_lshlrev_b32_e32 v216, 16, v227
	v_and_b32_e32 v217, 0xffff0000, v227
	v_pk_add_f32 v[216:217], v[216:217], 1.0 op_sel_hi:[1,0]
	v_lshlrev_b32_e32 v0, 16, v224
	v_pk_mul_f32 v[214:215], v[216:217], v[214:215]
	v_add_f32_e32 v0, 1.0, v0
	v_pk_mul_f32 v[24:25], v[24:25], v[214:215]
	v_rcp_f32_e32 v214, v0
	v_and_b32_e32 v0, 0xffff0000, v224
	v_add_f32_e32 v0, 1.0, v0
	v_rcp_f32_e32 v215, v0
	v_lshlrev_b32_e32 v216, 16, v228
	v_and_b32_e32 v217, 0xffff0000, v228
	v_pk_add_f32 v[216:217], v[216:217], 1.0 op_sel_hi:[1,0]
	v_lshlrev_b32_e32 v0, 16, v225
	v_pk_mul_f32 v[214:215], v[216:217], v[214:215]
	v_add_f32_e32 v0, 1.0, v0
	v_pk_mul_f32 v[18:19], v[18:19], v[214:215]
	v_rcp_f32_e32 v214, v0
	v_and_b32_e32 v0, 0xffff0000, v225
	v_add_f32_e32 v0, 1.0, v0
	v_rcp_f32_e32 v215, v0
	v_lshlrev_b32_e32 v216, 16, v229
	v_and_b32_e32 v217, 0xffff0000, v229
	v_pk_add_f32 v[216:217], v[216:217], 1.0 op_sel_hi:[1,0]
	s_waitcnt vmcnt(3)
	v_lshlrev_b32_e32 v0, 16, v230
	v_pk_mul_f32 v[214:215], v[216:217], v[214:215]
	v_add_f32_e32 v0, 1.0, v0
	v_pk_mul_f32 v[20:21], v[20:21], v[214:215]
	v_rcp_f32_e32 v214, v0
	v_and_b32_e32 v0, 0xffff0000, v230
	v_add_f32_e32 v0, 1.0, v0
	v_rcp_f32_e32 v215, v0
	s_waitcnt vmcnt(2)
	v_lshlrev_b32_e32 v216, 16, v240
	v_and_b32_e32 v217, 0xffff0000, v240
	v_pk_add_f32 v[216:217], v[216:217], 1.0 op_sel_hi:[1,0]
	v_lshlrev_b32_e32 v0, 16, v231
	v_pk_mul_f32 v[214:215], v[216:217], v[214:215]
	v_add_f32_e32 v0, 1.0, v0
	v_pk_mul_f32 v[14:15], v[14:15], v[214:215]
	v_rcp_f32_e32 v214, v0
	v_and_b32_e32 v0, 0xffff0000, v231
	v_add_f32_e32 v0, 1.0, v0
	v_rcp_f32_e32 v215, v0
	v_lshlrev_b32_e32 v216, 16, v241
	v_and_b32_e32 v217, 0xffff0000, v241
	v_pk_add_f32 v[216:217], v[216:217], 1.0 op_sel_hi:[1,0]
	v_lshlrev_b32_e32 v0, 16, v232
	v_pk_mul_f32 v[214:215], v[216:217], v[214:215]
	v_add_f32_e32 v0, 1.0, v0
	v_pk_mul_f32 v[16:17], v[16:17], v[214:215]
	v_rcp_f32_e32 v214, v0
	v_and_b32_e32 v0, 0xffff0000, v232
	v_add_f32_e32 v0, 1.0, v0
	v_rcp_f32_e32 v215, v0
	v_lshlrev_b32_e32 v216, 16, v242
	v_and_b32_e32 v217, 0xffff0000, v242
	v_pk_add_f32 v[216:217], v[216:217], 1.0 op_sel_hi:[1,0]
	v_lshlrev_b32_e32 v0, 16, v233
	v_pk_mul_f32 v[214:215], v[216:217], v[214:215]
	v_add_f32_e32 v0, 1.0, v0
	v_pk_mul_f32 v[10:11], v[10:11], v[214:215]
	v_rcp_f32_e32 v214, v0
	v_and_b32_e32 v0, 0xffff0000, v233
	v_add_f32_e32 v0, 1.0, v0
	v_rcp_f32_e32 v215, v0
	v_lshlrev_b32_e32 v216, 16, v243
	v_and_b32_e32 v217, 0xffff0000, v243
	v_pk_add_f32 v[216:217], v[216:217], 1.0 op_sel_hi:[1,0]
	s_waitcnt vmcnt(1)
	v_lshlrev_b32_e32 v0, 16, v244
	v_pk_mul_f32 v[214:215], v[216:217], v[214:215]
	v_add_f32_e32 v0, 1.0, v0
	v_pk_mul_f32 v[12:13], v[12:13], v[214:215]
	v_rcp_f32_e32 v214, v0
	v_and_b32_e32 v0, 0xffff0000, v244
	v_add_f32_e32 v0, 1.0, v0
	v_rcp_f32_e32 v215, v0
	s_waitcnt vmcnt(0)
	v_lshlrev_b32_e32 v216, 16, v248
	v_and_b32_e32 v217, 0xffff0000, v248
	v_pk_add_f32 v[216:217], v[216:217], 1.0 op_sel_hi:[1,0]
	v_lshlrev_b32_e32 v0, 16, v245
	v_pk_mul_f32 v[214:215], v[216:217], v[214:215]
	v_add_f32_e32 v0, 1.0, v0
	v_pk_mul_f32 v[6:7], v[6:7], v[214:215]
	v_rcp_f32_e32 v214, v0
	v_and_b32_e32 v0, 0xffff0000, v245
	v_add_f32_e32 v0, 1.0, v0
	v_rcp_f32_e32 v215, v0
	v_lshlrev_b32_e32 v216, 16, v249
	v_and_b32_e32 v217, 0xffff0000, v249
	v_pk_add_f32 v[216:217], v[216:217], 1.0 op_sel_hi:[1,0]
	v_lshlrev_b32_e32 v0, 16, v246
	v_pk_mul_f32 v[214:215], v[216:217], v[214:215]
	v_add_f32_e32 v0, 1.0, v0
	v_pk_mul_f32 v[8:9], v[8:9], v[214:215]
	v_rcp_f32_e32 v214, v0
	v_and_b32_e32 v0, 0xffff0000, v246
	v_add_f32_e32 v0, 1.0, v0
	v_rcp_f32_e32 v215, v0
	v_lshlrev_b32_e32 v216, 16, v250
	v_and_b32_e32 v217, 0xffff0000, v250
	v_pk_add_f32 v[216:217], v[216:217], 1.0 op_sel_hi:[1,0]
	v_lshlrev_b32_e32 v0, 16, v247
	v_pk_mul_f32 v[214:215], v[216:217], v[214:215]
	v_add_f32_e32 v0, 1.0, v0
	v_pk_mul_f32 v[2:3], v[2:3], v[214:215]
	v_rcp_f32_e32 v214, v0
	v_and_b32_e32 v0, 0xffff0000, v247
	v_add_f32_e32 v0, 1.0, v0
	v_rcp_f32_e32 v215, v0
	v_lshlrev_b32_e32 v216, 16, v251
	v_and_b32_e32 v217, 0xffff0000, v251
	v_pk_add_f32 v[216:217], v[216:217], 1.0 op_sel_hi:[1,0]
	s_nop 0
	v_pk_mul_f32 v[214:215], v[216:217], v[214:215]
	s_nop 0
	v_pk_mul_f32 v[4:5], v[4:5], v[214:215]
